# conv phase: sample-row items skip the 28 output rows nobody reads (868 of 992 multiply-adds per thread)
# speedup vs baseline: 1.0160x; 1.0067x over previous
.LBB0_930:
	global_load_dword v133, v[94:95], off
	global_load_dword v132, v[96:97], off
	global_load_dword v131, v[98:99], off
	global_load_dword v130, v[100:101], off
	global_load_dword v128, v[102:103], off
	global_load_dword v126, v[104:105], off
	global_load_dword v135, v[38:39], off
	global_load_dword v134, v[38:39], off offset:2048
	global_load_dword v129, v[40:41], off
	global_load_dword v127, v[42:43], off
	global_load_dword v125, v[44:45], off
	global_load_dword v124, v[46:47], off
	global_load_dword v123, v[48:49], off
	global_load_dword v122, v[50:51], off
	global_load_dword v121, v[52:53], off
	global_load_dword v16, v[54:55], off
	global_load_dword v15, v[56:57], off
	global_load_dword v14, v[58:59], off
	global_load_dword v13, v[60:61], off
	global_load_dword v12, v[62:63], off
	global_load_dword v11, v[64:65], off
	global_load_dword v10, v[66:67], off
	global_load_dword v9, v[68:69], off
	global_load_dword v8, v[70:71], off
	global_load_dword v7, v[72:73], off
	global_load_dword v6, v[74:75], off
	global_load_dword v5, v[76:77], off
	global_load_dword v4, v[78:79], off
	global_load_dword v3, v[80:81], off
	global_load_dword v2, v[82:83], off
	global_load_dword v0, v[84:85], off
	global_load_dword v1, v[86:87], off
	s_waitcnt vmcnt(0) lgkmcnt(0)
	s_barrier
	ds_read_u16 v136, v115
	ds_read_u16 v137, v115 offset:1024
	ds_read_u16 v138, v115 offset:57344
	ds_read_u16 v139, v115 offset:58368
	ds_read_u16 v191, v115 offset:59392
	ds_read_u16 v192, v115 offset:60416
	ds_read_u16 v193, v115 offset:61440
	ds_read_u16 v194, v115 offset:62464
	s_waitcnt lgkmcnt(7)
	v_lshlrev_b32_e32 v195, 16, v136
	s_waitcnt lgkmcnt(6)
	v_lshlrev_b32_e32 v196, 16, v137
	ds_read_u16 v136, v115 offset:2048
	ds_read_u16 v137, v115 offset:3072
	ds_read_u16 v140, v115 offset:4096
	ds_read_u16 v141, v115 offset:5120
	ds_read_u16 v142, v115 offset:6144
	ds_read_u16 v143, v115 offset:7168
	ds_read_u16 v144, v115 offset:8192
	ds_read_u16 v145, v115 offset:9216
	s_waitcnt lgkmcnt(7)
	v_lshlrev_b32_e32 v197, 16, v136
	s_waitcnt lgkmcnt(6)
	v_lshlrev_b32_e32 v198, 16, v137
	s_waitcnt lgkmcnt(5)
	v_lshlrev_b32_e32 v199, 16, v140
	s_waitcnt lgkmcnt(4)
	v_lshlrev_b32_e32 v200, 16, v141
	s_waitcnt lgkmcnt(3)
	v_lshlrev_b32_e32 v201, 16, v142
	s_waitcnt lgkmcnt(2)
	v_lshlrev_b32_e32 v190, 16, v143
	s_waitcnt lgkmcnt(1)
	v_lshlrev_b32_e32 v189, 16, v144
	s_waitcnt lgkmcnt(0)
	v_lshlrev_b32_e32 v188, 16, v145
	ds_read_u16 v136, v115 offset:10240
	ds_read_u16 v137, v115 offset:11264
	ds_read_u16 v140, v115 offset:12288
	ds_read_u16 v141, v115 offset:13312
	ds_read_u16 v142, v115 offset:14336
	ds_read_u16 v143, v115 offset:15360
	ds_read_u16 v144, v115 offset:16384
	ds_read_u16 v145, v115 offset:17408
	s_waitcnt lgkmcnt(7)
	v_lshlrev_b32_e32 v187, 16, v136
	s_waitcnt lgkmcnt(6)
	v_lshlrev_b32_e32 v186, 16, v137
	s_waitcnt lgkmcnt(5)
	v_lshlrev_b32_e32 v185, 16, v140
	s_waitcnt lgkmcnt(4)
	v_lshlrev_b32_e32 v184, 16, v141
	s_waitcnt lgkmcnt(3)
	v_lshlrev_b32_e32 v183, 16, v142
	s_waitcnt lgkmcnt(2)
	v_lshlrev_b32_e32 v182, 16, v143
	s_waitcnt lgkmcnt(1)
	v_lshlrev_b32_e32 v181, 16, v144
	s_waitcnt lgkmcnt(0)
	v_lshlrev_b32_e32 v180, 16, v145
	ds_read_u16 v136, v115 offset:18432
	ds_read_u16 v137, v115 offset:19456
	ds_read_u16 v140, v115 offset:20480
	ds_read_u16 v141, v115 offset:21504
	ds_read_u16 v142, v115 offset:22528
	ds_read_u16 v143, v115 offset:23552
	ds_read_u16 v144, v115 offset:24576
	ds_read_u16 v145, v115 offset:25600
	s_waitcnt lgkmcnt(7)
	v_lshlrev_b32_e32 v179, 16, v136
	s_waitcnt lgkmcnt(6)
	v_lshlrev_b32_e32 v178, 16, v137
	s_waitcnt lgkmcnt(5)
	v_lshlrev_b32_e32 v177, 16, v140
	s_waitcnt lgkmcnt(4)
	v_lshlrev_b32_e32 v176, 16, v141
	s_waitcnt lgkmcnt(3)
	v_lshlrev_b32_e32 v175, 16, v142
	s_waitcnt lgkmcnt(2)
	v_lshlrev_b32_e32 v174, 16, v143
	ds_read_u16 v136, v115 offset:26624
	ds_read_u16 v137, v115 offset:27648
	ds_read_u16 v140, v115 offset:28672
	ds_read_u16 v141, v115 offset:29696
	ds_read_u16 v142, v115 offset:30720
	ds_read_u16 v143, v115 offset:31744
	s_waitcnt lgkmcnt(7)
	v_lshlrev_b32_e32 v173, 16, v144
	s_waitcnt lgkmcnt(6)
	v_lshlrev_b32_e32 v172, 16, v145
	s_waitcnt lgkmcnt(5)
	v_lshlrev_b32_e32 v171, 16, v136
	s_waitcnt lgkmcnt(4)
	v_lshlrev_b32_e32 v170, 16, v137
	s_waitcnt lgkmcnt(3)
	v_lshlrev_b32_e32 v169, 16, v140
	s_waitcnt lgkmcnt(2)
	v_lshlrev_b32_e32 v168, 16, v141
	s_waitcnt lgkmcnt(1)
	v_lshlrev_b32_e32 v167, 16, v142
	s_waitcnt lgkmcnt(0)
	v_lshlrev_b32_e32 v142, 16, v143
	ds_read_u16 v136, v115 offset:32768
	ds_read_u16 v137, v115 offset:33792
	ds_read_u16 v140, v115 offset:34816
	ds_read_u16 v141, v115 offset:35840
	ds_read_u16 v143, v115 offset:36864
	ds_read_u16 v144, v115 offset:37888
	ds_read_u16 v145, v115 offset:38912
	ds_read_u16 v147, v115 offset:39936
	s_waitcnt lgkmcnt(7)
	v_lshlrev_b32_e32 v164, 16, v136
	s_waitcnt lgkmcnt(6)
	v_lshlrev_b32_e32 v161, 16, v137
	s_waitcnt lgkmcnt(5)
	v_lshlrev_b32_e32 v158, 16, v140
	s_waitcnt lgkmcnt(4)
	v_lshlrev_b32_e32 v155, 16, v141
	s_waitcnt lgkmcnt(3)
	v_lshlrev_b32_e32 v152, 16, v143
	s_waitcnt lgkmcnt(2)
	v_lshlrev_b32_e32 v149, 16, v144
	s_waitcnt lgkmcnt(1)
	v_lshlrev_b32_e32 v146, 16, v145
	s_waitcnt lgkmcnt(0)
	v_lshlrev_b32_e32 v143, 16, v147
	ds_read_u16 v136, v115 offset:40960
	ds_read_u16 v137, v115 offset:41984
	ds_read_u16 v140, v115 offset:43008
	ds_read_u16 v141, v115 offset:44032
	ds_read_u16 v144, v115 offset:45056
	ds_read_u16 v145, v115 offset:46080
	ds_read_u16 v147, v115 offset:47104
	ds_read_u16 v148, v115 offset:48128
	s_waitcnt lgkmcnt(7)
	v_lshlrev_b32_e32 v165, 16, v136
	s_waitcnt lgkmcnt(6)
	v_lshlrev_b32_e32 v162, 16, v137
	s_waitcnt lgkmcnt(5)
	v_lshlrev_b32_e32 v159, 16, v140
	s_waitcnt lgkmcnt(4)
	v_lshlrev_b32_e32 v156, 16, v141
	s_waitcnt lgkmcnt(3)
	v_lshlrev_b32_e32 v153, 16, v144
	s_waitcnt lgkmcnt(2)
	v_lshlrev_b32_e32 v150, 16, v145
	s_waitcnt lgkmcnt(0)
	v_lshlrev_b32_e32 v144, 16, v148
	ds_read_u16 v136, v115 offset:49152
	ds_read_u16 v137, v115 offset:50176
	ds_read_u16 v140, v115 offset:51200
	ds_read_u16 v141, v115 offset:52224
	ds_read_u16 v145, v115 offset:53248
	ds_read_u16 v148, v115 offset:54272
	ds_read_u16 v202, v115 offset:55296
	ds_read_u16 v203, v115 offset:56320
	s_waitcnt lgkmcnt(5)
	v_lshlrev_b32_e32 v160, 16, v140
	s_waitcnt lgkmcnt(4)
	v_lshlrev_b32_e32 v157, 16, v141
	v_lshlrev_b32_e32 v141, 16, v138
	v_lshlrev_b32_e32 v140, 16, v139
	v_lshlrev_b32_e32 v139, 16, v191
	v_lshlrev_b32_e32 v138, 16, v192
	v_lshlrev_b32_e32 v147, 16, v147
	v_lshlrev_b32_e32 v166, 16, v136
	v_lshlrev_b32_e32 v163, 16, v137
	s_waitcnt lgkmcnt(3)
	v_lshlrev_b32_e32 v154, 16, v145
	s_waitcnt lgkmcnt(2)
	v_lshlrev_b32_e32 v151, 16, v148
	s_waitcnt lgkmcnt(1)
	v_lshlrev_b32_e32 v148, 16, v202
	s_waitcnt lgkmcnt(0)
	v_lshlrev_b32_e32 v145, 16, v203
	v_lshlrev_b32_e32 v137, 16, v193
	v_lshlrev_b32_e32 v136, 16, v194
	s_cmp_ge_u32 s60, s13
	v_fma_f32 v191, v135, v195, v1
	v_fma_f32 v192, v135, v196, v1
	v_fmac_f32_e32 v191, v134, v196
	v_fmac_f32_e32 v192, v134, v197
	v_fmac_f32_e32 v191, v133, v197
	v_fmac_f32_e32 v192, v133, v198
	v_fmac_f32_e32 v191, v132, v198
	v_fmac_f32_e32 v192, v132, v199
	v_fmac_f32_e32 v191, v131, v199
	v_fmac_f32_e32 v192, v131, v200
	v_fmac_f32_e32 v191, v130, v200
	v_fmac_f32_e32 v192, v130, v201
	v_fmac_f32_e32 v191, v128, v201
	v_fmac_f32_e32 v192, v128, v190
	v_fmac_f32_e32 v191, v126, v190
	v_fmac_f32_e32 v192, v126, v189
	v_fmac_f32_e32 v191, v129, v189
	v_fmac_f32_e32 v192, v129, v188
	v_fmac_f32_e32 v191, v127, v188
	v_fmac_f32_e32 v192, v127, v187
	v_fmac_f32_e32 v191, v125, v187
	v_fmac_f32_e32 v192, v125, v186
	v_fmac_f32_e32 v191, v124, v186
	v_fmac_f32_e32 v192, v124, v185
	v_fmac_f32_e32 v191, v123, v185
	v_fmac_f32_e32 v192, v123, v184
	v_fmac_f32_e32 v191, v122, v184
	v_fmac_f32_e32 v192, v122, v183
	v_fmac_f32_e32 v191, v121, v183
	v_fmac_f32_e32 v192, v121, v182
	v_fmac_f32_e32 v191, v16, v182
	v_fmac_f32_e32 v192, v16, v181
	v_fmac_f32_e32 v191, v15, v181
	v_fmac_f32_e32 v192, v15, v180
	v_fmac_f32_e32 v191, v14, v180
	v_fmac_f32_e32 v192, v14, v179
	v_fmac_f32_e32 v191, v13, v179
	v_fmac_f32_e32 v192, v13, v178
	v_fmac_f32_e32 v191, v12, v178
	v_fmac_f32_e32 v192, v12, v177
	v_fmac_f32_e32 v191, v11, v177
	v_fmac_f32_e32 v192, v11, v176
	v_fmac_f32_e32 v191, v10, v176
	v_fmac_f32_e32 v192, v10, v175
	v_fmac_f32_e32 v191, v9, v175
	v_fmac_f32_e32 v192, v9, v174
	v_fmac_f32_e32 v191, v8, v174
	v_fmac_f32_e32 v192, v8, v173
	v_fmac_f32_e32 v191, v7, v173
	v_fmac_f32_e32 v192, v7, v172
	v_fmac_f32_e32 v191, v6, v172
	v_fmac_f32_e32 v192, v6, v171
	v_fmac_f32_e32 v191, v5, v171
	v_fmac_f32_e32 v192, v5, v170
	v_fmac_f32_e32 v191, v4, v170
	v_fmac_f32_e32 v192, v4, v169
	v_fmac_f32_e32 v191, v3, v169
	v_fmac_f32_e32 v192, v3, v168
	v_fmac_f32_e32 v191, v2, v168
	v_fmac_f32_e32 v192, v2, v167
	v_fmac_f32_e32 v191, v0, v167
	v_fmac_f32_e32 v192, v0, v142
	ds_write2st64_b32 v116, v191, v192 offset1:8
	v_fma_f32 v191, v135, v197, v1
	v_fma_f32 v192, v135, v198, v1
	v_fmac_f32_e32 v191, v134, v198
	v_fmac_f32_e32 v192, v134, v199
	v_fmac_f32_e32 v191, v133, v199
	v_fmac_f32_e32 v192, v133, v200
	v_fmac_f32_e32 v191, v132, v200
	v_fmac_f32_e32 v192, v132, v201
	v_fmac_f32_e32 v191, v131, v201
	v_fmac_f32_e32 v192, v131, v190
	v_fmac_f32_e32 v191, v130, v190
	v_fmac_f32_e32 v192, v130, v189
	v_fmac_f32_e32 v191, v128, v189
	v_fmac_f32_e32 v192, v128, v188
	v_fmac_f32_e32 v191, v126, v188
	v_fmac_f32_e32 v192, v126, v187
	v_fmac_f32_e32 v191, v129, v187
	v_fmac_f32_e32 v192, v129, v186
	v_fmac_f32_e32 v191, v127, v186
	v_fmac_f32_e32 v192, v127, v185
	v_fmac_f32_e32 v191, v125, v185
	v_fmac_f32_e32 v192, v125, v184
	v_fmac_f32_e32 v191, v124, v184
	v_fmac_f32_e32 v192, v124, v183
	v_fmac_f32_e32 v191, v123, v183
	v_fmac_f32_e32 v192, v123, v182
	v_fmac_f32_e32 v191, v122, v182
	v_fmac_f32_e32 v192, v122, v181
	v_fmac_f32_e32 v191, v121, v181
	v_fmac_f32_e32 v192, v121, v180
	v_fmac_f32_e32 v191, v16, v180
	v_fmac_f32_e32 v192, v16, v179
	v_fmac_f32_e32 v191, v15, v179
	v_fmac_f32_e32 v192, v15, v178
	v_fmac_f32_e32 v191, v14, v178
	v_fmac_f32_e32 v192, v14, v177
	v_fmac_f32_e32 v191, v13, v177
	v_fmac_f32_e32 v192, v13, v176
	v_fmac_f32_e32 v191, v12, v176
	v_fmac_f32_e32 v192, v12, v175
	v_fmac_f32_e32 v191, v11, v175
	v_fmac_f32_e32 v192, v11, v174
	v_fmac_f32_e32 v191, v10, v174
	v_fmac_f32_e32 v192, v10, v173
	v_fmac_f32_e32 v191, v9, v173
	v_fmac_f32_e32 v192, v9, v172
	v_fmac_f32_e32 v191, v8, v172
	v_fmac_f32_e32 v192, v8, v171
	v_fmac_f32_e32 v191, v7, v171
	v_fmac_f32_e32 v192, v7, v170
	v_fmac_f32_e32 v191, v6, v170
	v_fmac_f32_e32 v192, v6, v169
	v_fmac_f32_e32 v191, v5, v169
	v_fmac_f32_e32 v192, v5, v168
	v_fmac_f32_e32 v191, v4, v168
	v_fmac_f32_e32 v192, v4, v167
	v_fmac_f32_e32 v191, v3, v167
	v_fmac_f32_e32 v192, v3, v142
	v_fmac_f32_e32 v191, v2, v142
	v_fmac_f32_e32 v192, v2, v164
	v_fmac_f32_e32 v191, v0, v164
	v_fmac_f32_e32 v192, v0, v161
	ds_write2st64_b32 v116, v191, v192 offset0:16 offset1:24
	s_cmp_eq_u32 s13, 4
	s_cbranch_scc1 .Lmy_conv_skip
	v_fma_f32 v191, v135, v199, v1
	v_fma_f32 v192, v135, v200, v1
	v_fmac_f32_e32 v191, v134, v200
	v_fmac_f32_e32 v192, v134, v201
	v_fmac_f32_e32 v191, v133, v201
	v_fmac_f32_e32 v192, v133, v190
	v_fmac_f32_e32 v191, v132, v190
	v_fmac_f32_e32 v192, v132, v189
	v_fmac_f32_e32 v191, v131, v189
	v_fmac_f32_e32 v192, v131, v188
	v_fmac_f32_e32 v191, v130, v188
	v_fmac_f32_e32 v192, v130, v187
	v_fmac_f32_e32 v191, v128, v187
	v_fmac_f32_e32 v192, v128, v186
	v_fmac_f32_e32 v191, v126, v186
	v_fmac_f32_e32 v192, v126, v185
	v_fmac_f32_e32 v191, v129, v185
	v_fmac_f32_e32 v192, v129, v184
	v_fmac_f32_e32 v191, v127, v184
	v_fmac_f32_e32 v192, v127, v183
	v_fmac_f32_e32 v191, v125, v183
	v_fmac_f32_e32 v192, v125, v182
	v_fmac_f32_e32 v191, v124, v182
	v_fmac_f32_e32 v192, v124, v181
	v_fmac_f32_e32 v191, v123, v181
	v_fmac_f32_e32 v192, v123, v180
	v_fmac_f32_e32 v191, v122, v180
	v_fmac_f32_e32 v192, v122, v179
	v_fmac_f32_e32 v191, v121, v179
	v_fmac_f32_e32 v192, v121, v178
	v_fmac_f32_e32 v191, v16, v178
	v_fmac_f32_e32 v192, v16, v177
	v_fmac_f32_e32 v191, v15, v177
	v_fmac_f32_e32 v192, v15, v176
	v_fmac_f32_e32 v191, v14, v176
	v_fmac_f32_e32 v192, v14, v175
	v_fmac_f32_e32 v191, v13, v175
	v_fmac_f32_e32 v192, v13, v174
	v_fmac_f32_e32 v191, v12, v174
	v_fmac_f32_e32 v192, v12, v173
	v_fmac_f32_e32 v191, v11, v173
	v_fmac_f32_e32 v192, v11, v172
	v_fmac_f32_e32 v191, v10, v172
	v_fmac_f32_e32 v192, v10, v171
	v_fmac_f32_e32 v191, v9, v171
	v_fmac_f32_e32 v192, v9, v170
	v_fmac_f32_e32 v191, v8, v170
	v_fmac_f32_e32 v192, v8, v169
	v_fmac_f32_e32 v191, v7, v169
	v_fmac_f32_e32 v192, v7, v168
	v_fmac_f32_e32 v191, v6, v168
	v_fmac_f32_e32 v192, v6, v167
	v_fmac_f32_e32 v191, v5, v167
	v_fmac_f32_e32 v192, v5, v142
	v_fmac_f32_e32 v191, v4, v142
	v_fmac_f32_e32 v192, v4, v164
	v_fmac_f32_e32 v191, v3, v164
	v_fmac_f32_e32 v192, v3, v161
	v_fmac_f32_e32 v191, v2, v161
	v_fmac_f32_e32 v192, v2, v158
	v_fmac_f32_e32 v191, v0, v158
	v_fmac_f32_e32 v192, v0, v155
	ds_write2st64_b32 v116, v191, v192 offset0:32 offset1:40
	v_fma_f32 v191, v135, v201, v1
	v_fmac_f32_e32 v191, v134, v190
	v_fma_f32 v190, v135, v190, v1
	v_fmac_f32_e32 v191, v133, v189
	v_fmac_f32_e32 v190, v134, v189
	v_fma_f32 v189, v135, v189, v1
	v_fmac_f32_e32 v191, v132, v188
	v_fmac_f32_e32 v190, v133, v188
	v_fmac_f32_e32 v189, v134, v188
	v_fma_f32 v188, v135, v188, v1
	v_fmac_f32_e32 v191, v131, v187
	v_fmac_f32_e32 v190, v132, v187
	v_fmac_f32_e32 v189, v133, v187
	v_fmac_f32_e32 v188, v134, v187
	v_fma_f32 v187, v135, v187, v1
	v_fmac_f32_e32 v191, v130, v186
	v_fmac_f32_e32 v190, v131, v186
	v_fmac_f32_e32 v189, v132, v186
	v_fmac_f32_e32 v188, v133, v186
	v_fmac_f32_e32 v187, v134, v186
	v_fma_f32 v186, v135, v186, v1
	v_fmac_f32_e32 v191, v128, v185
	v_fmac_f32_e32 v190, v130, v185
	v_fmac_f32_e32 v189, v131, v185
	v_fmac_f32_e32 v188, v132, v185
	v_fmac_f32_e32 v187, v133, v185
	v_fmac_f32_e32 v186, v134, v185
	v_fma_f32 v185, v135, v185, v1
	v_fmac_f32_e32 v191, v126, v184
	v_fmac_f32_e32 v190, v128, v184
	v_fmac_f32_e32 v189, v130, v184
	v_fmac_f32_e32 v188, v131, v184
	v_fmac_f32_e32 v187, v132, v184
	v_fmac_f32_e32 v186, v133, v184
	v_fmac_f32_e32 v185, v134, v184
	v_fma_f32 v184, v135, v184, v1
	v_fmac_f32_e32 v191, v129, v183
	v_fmac_f32_e32 v190, v126, v183
	v_fmac_f32_e32 v189, v128, v183
	v_fmac_f32_e32 v188, v130, v183
	v_fmac_f32_e32 v187, v131, v183
	v_fmac_f32_e32 v186, v132, v183
	v_fmac_f32_e32 v185, v133, v183
	v_fmac_f32_e32 v184, v134, v183
	v_fma_f32 v183, v135, v183, v1
	v_fmac_f32_e32 v191, v127, v182
	v_fmac_f32_e32 v190, v129, v182
	v_fmac_f32_e32 v189, v126, v182
	v_fmac_f32_e32 v188, v128, v182
	v_fmac_f32_e32 v187, v130, v182
	v_fmac_f32_e32 v186, v131, v182
	v_fmac_f32_e32 v185, v132, v182
	v_fmac_f32_e32 v184, v133, v182
	v_fmac_f32_e32 v183, v134, v182
	v_fma_f32 v182, v135, v182, v1
	v_fmac_f32_e32 v191, v125, v181
	v_fmac_f32_e32 v190, v127, v181
	v_fmac_f32_e32 v189, v129, v181
	v_fmac_f32_e32 v188, v126, v181
	v_fmac_f32_e32 v187, v128, v181
	v_fmac_f32_e32 v186, v130, v181
	v_fmac_f32_e32 v185, v131, v181
	v_fmac_f32_e32 v184, v132, v181
	v_fmac_f32_e32 v183, v133, v181
	v_fmac_f32_e32 v182, v134, v181
	v_fma_f32 v181, v135, v181, v1
	v_fmac_f32_e32 v191, v124, v180
	v_fmac_f32_e32 v190, v125, v180
	v_fmac_f32_e32 v189, v127, v180
	v_fmac_f32_e32 v188, v129, v180
	v_fmac_f32_e32 v187, v126, v180
	v_fmac_f32_e32 v186, v128, v180
	v_fmac_f32_e32 v185, v130, v180
	v_fmac_f32_e32 v184, v131, v180
	v_fmac_f32_e32 v183, v132, v180
	v_fmac_f32_e32 v182, v133, v180
	v_fmac_f32_e32 v181, v134, v180
	v_fma_f32 v180, v135, v180, v1
	v_fmac_f32_e32 v191, v123, v179
	v_fmac_f32_e32 v190, v124, v179
	v_fmac_f32_e32 v189, v125, v179
	v_fmac_f32_e32 v188, v127, v179
	v_fmac_f32_e32 v187, v129, v179
	v_fmac_f32_e32 v186, v126, v179
	v_fmac_f32_e32 v185, v128, v179
	v_fmac_f32_e32 v184, v130, v179
	v_fmac_f32_e32 v183, v131, v179
	v_fmac_f32_e32 v182, v132, v179
	v_fmac_f32_e32 v181, v133, v179
	v_fmac_f32_e32 v180, v134, v179
	v_fma_f32 v179, v135, v179, v1
	v_fmac_f32_e32 v191, v122, v178
	v_fmac_f32_e32 v190, v123, v178
	v_fmac_f32_e32 v189, v124, v178
	v_fmac_f32_e32 v188, v125, v178
	v_fmac_f32_e32 v187, v127, v178
	v_fmac_f32_e32 v186, v129, v178
	v_fmac_f32_e32 v185, v126, v178
	v_fmac_f32_e32 v184, v128, v178
	v_fmac_f32_e32 v183, v130, v178
	v_fmac_f32_e32 v182, v131, v178
	v_fmac_f32_e32 v181, v132, v178
	v_fmac_f32_e32 v180, v133, v178
	v_fmac_f32_e32 v179, v134, v178
	v_fma_f32 v178, v135, v178, v1
	v_fmac_f32_e32 v191, v121, v177
	v_fmac_f32_e32 v190, v122, v177
	v_fmac_f32_e32 v189, v123, v177
	v_fmac_f32_e32 v188, v124, v177
	v_fmac_f32_e32 v187, v125, v177
	v_fmac_f32_e32 v186, v127, v177
	v_fmac_f32_e32 v185, v129, v177
	v_fmac_f32_e32 v184, v126, v177
	v_fmac_f32_e32 v183, v128, v177
	v_fmac_f32_e32 v182, v130, v177
	v_fmac_f32_e32 v181, v131, v177
	v_fmac_f32_e32 v180, v132, v177
	v_fmac_f32_e32 v179, v133, v177
	v_fmac_f32_e32 v178, v134, v177
	v_fma_f32 v177, v135, v177, v1
	v_fmac_f32_e32 v191, v16, v176
	v_fmac_f32_e32 v190, v121, v176
	v_fmac_f32_e32 v189, v122, v176
	v_fmac_f32_e32 v188, v123, v176
	v_fmac_f32_e32 v187, v124, v176
	v_fmac_f32_e32 v186, v125, v176
	v_fmac_f32_e32 v185, v127, v176
	v_fmac_f32_e32 v184, v129, v176
	v_fmac_f32_e32 v183, v126, v176
	v_fmac_f32_e32 v182, v128, v176
	v_fmac_f32_e32 v181, v130, v176
	v_fmac_f32_e32 v180, v131, v176
	v_fmac_f32_e32 v179, v132, v176
	v_fmac_f32_e32 v178, v133, v176
	v_fmac_f32_e32 v177, v134, v176
	v_fma_f32 v176, v135, v176, v1
	v_fmac_f32_e32 v191, v15, v175
	v_fmac_f32_e32 v190, v16, v175
	v_fmac_f32_e32 v189, v121, v175
	v_fmac_f32_e32 v188, v122, v175
	v_fmac_f32_e32 v187, v123, v175
	v_fmac_f32_e32 v186, v124, v175
	v_fmac_f32_e32 v185, v125, v175
	v_fmac_f32_e32 v184, v127, v175
	v_fmac_f32_e32 v183, v129, v175
	v_fmac_f32_e32 v182, v126, v175
	v_fmac_f32_e32 v181, v128, v175
	v_fmac_f32_e32 v180, v130, v175
	v_fmac_f32_e32 v179, v131, v175
	v_fmac_f32_e32 v178, v132, v175
	v_fmac_f32_e32 v177, v133, v175
	v_fmac_f32_e32 v176, v134, v175
	v_fma_f32 v175, v135, v175, v1
	v_fmac_f32_e32 v191, v14, v174
	v_fmac_f32_e32 v190, v15, v174
	v_fmac_f32_e32 v189, v16, v174
	v_fmac_f32_e32 v188, v121, v174
	v_fmac_f32_e32 v187, v122, v174
	v_fmac_f32_e32 v186, v123, v174
	v_fmac_f32_e32 v185, v124, v174
	v_fmac_f32_e32 v184, v125, v174
	v_fmac_f32_e32 v183, v127, v174
	v_fmac_f32_e32 v182, v129, v174
	v_fmac_f32_e32 v181, v126, v174
	v_fmac_f32_e32 v180, v128, v174
	v_fmac_f32_e32 v179, v130, v174
	v_fmac_f32_e32 v178, v131, v174
	v_fmac_f32_e32 v177, v132, v174
	v_fmac_f32_e32 v176, v133, v174
	v_fmac_f32_e32 v175, v134, v174
	v_fma_f32 v174, v135, v174, v1
	v_fmac_f32_e32 v191, v13, v173
	v_fmac_f32_e32 v190, v14, v173
	v_fmac_f32_e32 v189, v15, v173
	v_fmac_f32_e32 v188, v16, v173
	v_fmac_f32_e32 v187, v121, v173
	v_fmac_f32_e32 v186, v122, v173
	v_fmac_f32_e32 v185, v123, v173
	v_fmac_f32_e32 v184, v124, v173
	v_fmac_f32_e32 v183, v125, v173
	v_fmac_f32_e32 v182, v127, v173
	v_fmac_f32_e32 v181, v129, v173
	v_fmac_f32_e32 v180, v126, v173
	v_fmac_f32_e32 v179, v128, v173
	v_fmac_f32_e32 v178, v130, v173
	v_fmac_f32_e32 v177, v131, v173
	v_fmac_f32_e32 v176, v132, v173
	v_fmac_f32_e32 v175, v133, v173
	v_fmac_f32_e32 v174, v134, v173
	v_fma_f32 v173, v135, v173, v1
	v_fmac_f32_e32 v191, v12, v172
	v_fmac_f32_e32 v190, v13, v172
	v_fmac_f32_e32 v189, v14, v172
	v_fmac_f32_e32 v188, v15, v172
	v_fmac_f32_e32 v187, v16, v172
	v_fmac_f32_e32 v186, v121, v172
	v_fmac_f32_e32 v185, v122, v172
	v_fmac_f32_e32 v184, v123, v172
	v_fmac_f32_e32 v183, v124, v172
	v_fmac_f32_e32 v182, v125, v172
	v_fmac_f32_e32 v181, v127, v172
	v_fmac_f32_e32 v180, v129, v172
	v_fmac_f32_e32 v179, v126, v172
	v_fmac_f32_e32 v178, v128, v172
	v_fmac_f32_e32 v177, v130, v172
	v_fmac_f32_e32 v176, v131, v172
	v_fmac_f32_e32 v175, v132, v172
	v_fmac_f32_e32 v174, v133, v172
	v_fmac_f32_e32 v173, v134, v172
	v_fma_f32 v172, v135, v172, v1
	v_fmac_f32_e32 v191, v11, v171
	v_fmac_f32_e32 v190, v12, v171
	v_fmac_f32_e32 v189, v13, v171
	v_fmac_f32_e32 v188, v14, v171
	v_fmac_f32_e32 v187, v15, v171
	v_fmac_f32_e32 v186, v16, v171
	v_fmac_f32_e32 v185, v121, v171
	v_fmac_f32_e32 v184, v122, v171
	v_fmac_f32_e32 v183, v123, v171
	v_fmac_f32_e32 v182, v124, v171
	v_fmac_f32_e32 v181, v125, v171
	v_fmac_f32_e32 v180, v127, v171
	v_fmac_f32_e32 v179, v129, v171
	v_fmac_f32_e32 v178, v126, v171
	v_fmac_f32_e32 v177, v128, v171
	v_fmac_f32_e32 v176, v130, v171
	v_fmac_f32_e32 v175, v131, v171
	v_fmac_f32_e32 v174, v132, v171
	v_fmac_f32_e32 v173, v133, v171
	v_fmac_f32_e32 v172, v134, v171
	v_fma_f32 v171, v135, v171, v1
	v_fmac_f32_e32 v191, v10, v170
	v_fmac_f32_e32 v190, v11, v170
	v_fmac_f32_e32 v189, v12, v170
	v_fmac_f32_e32 v188, v13, v170
	v_fmac_f32_e32 v187, v14, v170
	v_fmac_f32_e32 v186, v15, v170
	v_fmac_f32_e32 v185, v16, v170
	v_fmac_f32_e32 v184, v121, v170
	v_fmac_f32_e32 v183, v122, v170
	v_fmac_f32_e32 v182, v123, v170
	v_fmac_f32_e32 v181, v124, v170
	v_fmac_f32_e32 v180, v125, v170
	v_fmac_f32_e32 v179, v127, v170
	v_fmac_f32_e32 v178, v129, v170
	v_fmac_f32_e32 v177, v126, v170
	v_fmac_f32_e32 v176, v128, v170
	v_fmac_f32_e32 v175, v130, v170
	v_fmac_f32_e32 v174, v131, v170
	v_fmac_f32_e32 v173, v132, v170
	v_fmac_f32_e32 v172, v133, v170
	v_fmac_f32_e32 v171, v134, v170
	v_fma_f32 v170, v135, v170, v1
	v_fmac_f32_e32 v191, v9, v169
	v_fmac_f32_e32 v190, v10, v169
	v_fmac_f32_e32 v189, v11, v169
	v_fmac_f32_e32 v188, v12, v169
	v_fmac_f32_e32 v187, v13, v169
	v_fmac_f32_e32 v186, v14, v169
	v_fmac_f32_e32 v185, v15, v169
	v_fmac_f32_e32 v184, v16, v169
	v_fmac_f32_e32 v183, v121, v169
	v_fmac_f32_e32 v182, v122, v169
	v_fmac_f32_e32 v181, v123, v169
	v_fmac_f32_e32 v180, v124, v169
	v_fmac_f32_e32 v179, v125, v169
	v_fmac_f32_e32 v178, v127, v169
	v_fmac_f32_e32 v177, v129, v169
	v_fmac_f32_e32 v176, v126, v169
	v_fmac_f32_e32 v175, v128, v169
	v_fmac_f32_e32 v174, v130, v169
	v_fmac_f32_e32 v173, v131, v169
	v_fmac_f32_e32 v172, v132, v169
	v_fmac_f32_e32 v171, v133, v169
	v_fmac_f32_e32 v170, v134, v169
	v_fma_f32 v169, v135, v169, v1
	v_fmac_f32_e32 v191, v8, v168
	v_fmac_f32_e32 v190, v9, v168
	v_fmac_f32_e32 v189, v10, v168
	v_fmac_f32_e32 v188, v11, v168
	v_fmac_f32_e32 v187, v12, v168
	v_fmac_f32_e32 v186, v13, v168
	v_fmac_f32_e32 v185, v14, v168
	v_fmac_f32_e32 v184, v15, v168
	v_fmac_f32_e32 v183, v16, v168
	v_fmac_f32_e32 v182, v121, v168
	v_fmac_f32_e32 v181, v122, v168
	v_fmac_f32_e32 v180, v123, v168
	v_fmac_f32_e32 v179, v124, v168
	v_fmac_f32_e32 v178, v125, v168
	v_fmac_f32_e32 v177, v127, v168
	v_fmac_f32_e32 v176, v129, v168
	v_fmac_f32_e32 v175, v126, v168
	v_fmac_f32_e32 v174, v128, v168
	v_fmac_f32_e32 v173, v130, v168
	v_fmac_f32_e32 v172, v131, v168
	v_fmac_f32_e32 v171, v132, v168
	v_fmac_f32_e32 v170, v133, v168
	v_fmac_f32_e32 v169, v134, v168
	v_fma_f32 v168, v135, v168, v1
	v_fmac_f32_e32 v191, v7, v167
	v_fmac_f32_e32 v190, v8, v167
	v_fmac_f32_e32 v189, v9, v167
	v_fmac_f32_e32 v188, v10, v167
	v_fmac_f32_e32 v187, v11, v167
	v_fmac_f32_e32 v186, v12, v167
	v_fmac_f32_e32 v185, v13, v167
	v_fmac_f32_e32 v184, v14, v167
	v_fmac_f32_e32 v183, v15, v167
	v_fmac_f32_e32 v182, v16, v167
	v_fmac_f32_e32 v181, v121, v167
	v_fmac_f32_e32 v180, v122, v167
	v_fmac_f32_e32 v179, v123, v167
	v_fmac_f32_e32 v178, v124, v167
	v_fmac_f32_e32 v177, v125, v167
	v_fmac_f32_e32 v176, v127, v167
	v_fmac_f32_e32 v175, v129, v167
	v_fmac_f32_e32 v174, v126, v167
	v_fmac_f32_e32 v173, v128, v167
	v_fmac_f32_e32 v172, v130, v167
	v_fmac_f32_e32 v171, v131, v167
	v_fmac_f32_e32 v170, v132, v167
	v_fmac_f32_e32 v169, v133, v167
	v_fmac_f32_e32 v168, v134, v167
	v_fma_f32 v167, v135, v167, v1
	v_fmac_f32_e32 v1, v135, v142
	v_fmac_f32_e32 v167, v134, v142
	v_fmac_f32_e32 v1, v134, v164
	v_fmac_f32_e32 v168, v133, v142
	v_fmac_f32_e32 v167, v133, v164
	v_fmac_f32_e32 v1, v133, v161
	v_fmac_f32_e32 v169, v132, v142
	v_fmac_f32_e32 v168, v132, v164
	v_fmac_f32_e32 v167, v132, v161
	v_fmac_f32_e32 v1, v132, v158
	v_fmac_f32_e32 v170, v131, v142
	v_fmac_f32_e32 v169, v131, v164
	v_fmac_f32_e32 v168, v131, v161
	v_fmac_f32_e32 v167, v131, v158
	v_fmac_f32_e32 v1, v131, v155
	v_fmac_f32_e32 v171, v130, v142
	v_fmac_f32_e32 v170, v130, v164
	v_fmac_f32_e32 v169, v130, v161
	v_fmac_f32_e32 v168, v130, v158
	v_fmac_f32_e32 v167, v130, v155
	v_fmac_f32_e32 v1, v130, v152
	v_fmac_f32_e32 v172, v128, v142
	v_fmac_f32_e32 v171, v128, v164
	v_fmac_f32_e32 v170, v128, v161
	v_fmac_f32_e32 v169, v128, v158
	v_fmac_f32_e32 v168, v128, v155
	v_fmac_f32_e32 v167, v128, v152
	v_fmac_f32_e32 v1, v128, v149
	v_fmac_f32_e32 v173, v126, v142
	v_fmac_f32_e32 v172, v126, v164
	v_fmac_f32_e32 v171, v126, v161
	v_fmac_f32_e32 v170, v126, v158
	v_fmac_f32_e32 v169, v126, v155
	v_fmac_f32_e32 v168, v126, v152
	v_fmac_f32_e32 v167, v126, v149
	v_fmac_f32_e32 v1, v126, v146
	v_fmac_f32_e32 v174, v129, v142
	v_fmac_f32_e32 v173, v129, v164
	v_fmac_f32_e32 v172, v129, v161
	v_fmac_f32_e32 v171, v129, v158
	v_fmac_f32_e32 v170, v129, v155
	v_fmac_f32_e32 v169, v129, v152
	v_fmac_f32_e32 v168, v129, v149
	v_fmac_f32_e32 v167, v129, v146
	v_fmac_f32_e32 v1, v129, v143
	v_fmac_f32_e32 v175, v127, v142
	v_fmac_f32_e32 v174, v127, v164
	v_fmac_f32_e32 v173, v127, v161
	v_fmac_f32_e32 v172, v127, v158
	v_fmac_f32_e32 v171, v127, v155
	v_fmac_f32_e32 v170, v127, v152
	v_fmac_f32_e32 v169, v127, v149
	v_fmac_f32_e32 v168, v127, v146
	v_fmac_f32_e32 v167, v127, v143
	v_fmac_f32_e32 v1, v127, v165
	v_fmac_f32_e32 v176, v125, v142
	v_fmac_f32_e32 v175, v125, v164
	v_fmac_f32_e32 v174, v125, v161
	v_fmac_f32_e32 v173, v125, v158
	v_fmac_f32_e32 v172, v125, v155
	v_fmac_f32_e32 v171, v125, v152
	v_fmac_f32_e32 v170, v125, v149
	v_fmac_f32_e32 v169, v125, v146
	v_fmac_f32_e32 v168, v125, v143
	v_fmac_f32_e32 v167, v125, v165
	v_fmac_f32_e32 v1, v125, v162
	v_fmac_f32_e32 v177, v124, v142
	v_fmac_f32_e32 v176, v124, v164
	v_fmac_f32_e32 v175, v124, v161
	v_fmac_f32_e32 v174, v124, v158
	v_fmac_f32_e32 v173, v124, v155
	v_fmac_f32_e32 v172, v124, v152
	v_fmac_f32_e32 v171, v124, v149
	v_fmac_f32_e32 v170, v124, v146
	v_fmac_f32_e32 v169, v124, v143
	v_fmac_f32_e32 v168, v124, v165
	v_fmac_f32_e32 v167, v124, v162
	v_fmac_f32_e32 v1, v124, v159
	v_fmac_f32_e32 v178, v123, v142
	v_fmac_f32_e32 v177, v123, v164
	v_fmac_f32_e32 v176, v123, v161
	v_fmac_f32_e32 v175, v123, v158
	v_fmac_f32_e32 v174, v123, v155
	v_fmac_f32_e32 v173, v123, v152
	v_fmac_f32_e32 v172, v123, v149
	v_fmac_f32_e32 v171, v123, v146
	v_fmac_f32_e32 v170, v123, v143
	v_fmac_f32_e32 v169, v123, v165
	v_fmac_f32_e32 v168, v123, v162
	v_fmac_f32_e32 v167, v123, v159
	v_fmac_f32_e32 v1, v123, v156
	v_fmac_f32_e32 v179, v122, v142
	v_fmac_f32_e32 v178, v122, v164
	v_fmac_f32_e32 v177, v122, v161
	v_fmac_f32_e32 v176, v122, v158
	v_fmac_f32_e32 v175, v122, v155
	v_fmac_f32_e32 v174, v122, v152
	v_fmac_f32_e32 v173, v122, v149
	v_fmac_f32_e32 v172, v122, v146
	v_fmac_f32_e32 v171, v122, v143
	v_fmac_f32_e32 v170, v122, v165
	v_fmac_f32_e32 v169, v122, v162
	v_fmac_f32_e32 v168, v122, v159
	v_fmac_f32_e32 v167, v122, v156
	v_fmac_f32_e32 v1, v122, v153
	v_fmac_f32_e32 v180, v121, v142
	v_fmac_f32_e32 v179, v121, v164
	v_fmac_f32_e32 v178, v121, v161
	v_fmac_f32_e32 v177, v121, v158
	v_fmac_f32_e32 v176, v121, v155
	v_fmac_f32_e32 v175, v121, v152
	v_fmac_f32_e32 v174, v121, v149
	v_fmac_f32_e32 v173, v121, v146
	v_fmac_f32_e32 v172, v121, v143
	v_fmac_f32_e32 v171, v121, v165
	v_fmac_f32_e32 v170, v121, v162
	v_fmac_f32_e32 v169, v121, v159
	v_fmac_f32_e32 v168, v121, v156
	v_fmac_f32_e32 v167, v121, v153
	v_fmac_f32_e32 v1, v121, v150
	v_fmac_f32_e32 v181, v16, v142
	v_fmac_f32_e32 v180, v16, v164
	v_fmac_f32_e32 v179, v16, v161
	v_fmac_f32_e32 v178, v16, v158
	v_fmac_f32_e32 v177, v16, v155
	v_fmac_f32_e32 v176, v16, v152
	v_fmac_f32_e32 v175, v16, v149
	v_fmac_f32_e32 v174, v16, v146
	v_fmac_f32_e32 v173, v16, v143
	v_fmac_f32_e32 v172, v16, v165
	v_fmac_f32_e32 v171, v16, v162
	v_fmac_f32_e32 v170, v16, v159
	v_fmac_f32_e32 v169, v16, v156
	v_fmac_f32_e32 v168, v16, v153
	v_fmac_f32_e32 v167, v16, v150
	v_fmac_f32_e32 v1, v16, v147
	v_fmac_f32_e32 v182, v15, v142
	v_fmac_f32_e32 v181, v15, v164
	v_fmac_f32_e32 v180, v15, v161
	v_fmac_f32_e32 v179, v15, v158
	v_fmac_f32_e32 v178, v15, v155
	v_fmac_f32_e32 v177, v15, v152
	v_fmac_f32_e32 v176, v15, v149
	v_fmac_f32_e32 v175, v15, v146
	v_fmac_f32_e32 v174, v15, v143
	v_fmac_f32_e32 v173, v15, v165
	v_fmac_f32_e32 v172, v15, v162
	v_fmac_f32_e32 v171, v15, v159
	v_fmac_f32_e32 v170, v15, v156
	v_fmac_f32_e32 v169, v15, v153
	v_fmac_f32_e32 v168, v15, v150
	v_fmac_f32_e32 v167, v15, v147
	v_fmac_f32_e32 v1, v15, v144
	v_fmac_f32_e32 v183, v14, v142
	v_fmac_f32_e32 v182, v14, v164
	v_fmac_f32_e32 v181, v14, v161
	v_fmac_f32_e32 v180, v14, v158
	v_fmac_f32_e32 v179, v14, v155
	v_fmac_f32_e32 v178, v14, v152
	v_fmac_f32_e32 v177, v14, v149
	v_fmac_f32_e32 v176, v14, v146
	v_fmac_f32_e32 v175, v14, v143
	v_fmac_f32_e32 v174, v14, v165
	v_fmac_f32_e32 v173, v14, v162
	v_fmac_f32_e32 v172, v14, v159
	v_fmac_f32_e32 v171, v14, v156
	v_fmac_f32_e32 v170, v14, v153
	v_fmac_f32_e32 v169, v14, v150
	v_fmac_f32_e32 v168, v14, v147
	v_fmac_f32_e32 v167, v14, v144
	v_fmac_f32_e32 v1, v14, v166
	v_fmac_f32_e32 v184, v13, v142
	v_fmac_f32_e32 v183, v13, v164
	v_fmac_f32_e32 v182, v13, v161
	v_fmac_f32_e32 v181, v13, v158
	v_fmac_f32_e32 v180, v13, v155
	v_fmac_f32_e32 v179, v13, v152
	v_fmac_f32_e32 v178, v13, v149
	v_fmac_f32_e32 v177, v13, v146
	v_fmac_f32_e32 v176, v13, v143
	v_fmac_f32_e32 v175, v13, v165
	v_fmac_f32_e32 v174, v13, v162
	v_fmac_f32_e32 v173, v13, v159
	v_fmac_f32_e32 v172, v13, v156
	v_fmac_f32_e32 v171, v13, v153
	v_fmac_f32_e32 v170, v13, v150
	v_fmac_f32_e32 v169, v13, v147
	v_fmac_f32_e32 v168, v13, v144
	v_fmac_f32_e32 v167, v13, v166
	v_fmac_f32_e32 v1, v13, v163
	v_fmac_f32_e32 v185, v12, v142
	v_fmac_f32_e32 v184, v12, v164
	v_fmac_f32_e32 v183, v12, v161
	v_fmac_f32_e32 v182, v12, v158
	v_fmac_f32_e32 v181, v12, v155
	v_fmac_f32_e32 v180, v12, v152
	v_fmac_f32_e32 v179, v12, v149
	v_fmac_f32_e32 v178, v12, v146
	v_fmac_f32_e32 v177, v12, v143
	v_fmac_f32_e32 v176, v12, v165
	v_fmac_f32_e32 v175, v12, v162
	v_fmac_f32_e32 v174, v12, v159
	v_fmac_f32_e32 v173, v12, v156
	v_fmac_f32_e32 v172, v12, v153
	v_fmac_f32_e32 v171, v12, v150
	v_fmac_f32_e32 v170, v12, v147
	v_fmac_f32_e32 v169, v12, v144
	v_fmac_f32_e32 v168, v12, v166
	v_fmac_f32_e32 v167, v12, v163
	v_fmac_f32_e32 v1, v12, v160
	v_fmac_f32_e32 v186, v11, v142
	v_fmac_f32_e32 v185, v11, v164
	v_fmac_f32_e32 v184, v11, v161
	v_fmac_f32_e32 v183, v11, v158
	v_fmac_f32_e32 v182, v11, v155
	v_fmac_f32_e32 v181, v11, v152
	v_fmac_f32_e32 v180, v11, v149
	v_fmac_f32_e32 v179, v11, v146
	v_fmac_f32_e32 v178, v11, v143
	v_fmac_f32_e32 v177, v11, v165
	v_fmac_f32_e32 v176, v11, v162
	v_fmac_f32_e32 v175, v11, v159
	v_fmac_f32_e32 v174, v11, v156
	v_fmac_f32_e32 v173, v11, v153
	v_fmac_f32_e32 v172, v11, v150
	v_fmac_f32_e32 v171, v11, v147
	v_fmac_f32_e32 v170, v11, v144
	v_fmac_f32_e32 v169, v11, v166
	v_fmac_f32_e32 v168, v11, v163
	v_fmac_f32_e32 v167, v11, v160
	v_fmac_f32_e32 v1, v11, v157
	v_fmac_f32_e32 v187, v10, v142
	v_fmac_f32_e32 v186, v10, v164
	v_fmac_f32_e32 v185, v10, v161
	v_fmac_f32_e32 v184, v10, v158
	v_fmac_f32_e32 v183, v10, v155
	v_fmac_f32_e32 v182, v10, v152
	v_fmac_f32_e32 v181, v10, v149
	v_fmac_f32_e32 v180, v10, v146
	v_fmac_f32_e32 v179, v10, v143
	v_fmac_f32_e32 v178, v10, v165
	v_fmac_f32_e32 v177, v10, v162
	v_fmac_f32_e32 v176, v10, v159
	v_fmac_f32_e32 v175, v10, v156
	v_fmac_f32_e32 v174, v10, v153
	v_fmac_f32_e32 v173, v10, v150
	v_fmac_f32_e32 v172, v10, v147
	v_fmac_f32_e32 v171, v10, v144
	v_fmac_f32_e32 v170, v10, v166
	v_fmac_f32_e32 v169, v10, v163
	v_fmac_f32_e32 v168, v10, v160
	v_fmac_f32_e32 v167, v10, v157
	v_fmac_f32_e32 v1, v10, v154
	v_fmac_f32_e32 v188, v9, v142
	v_fmac_f32_e32 v187, v9, v164
	v_fmac_f32_e32 v186, v9, v161
	v_fmac_f32_e32 v185, v9, v158
	v_fmac_f32_e32 v184, v9, v155
	v_fmac_f32_e32 v183, v9, v152
	v_fmac_f32_e32 v182, v9, v149
	v_fmac_f32_e32 v181, v9, v146
	v_fmac_f32_e32 v180, v9, v143
	v_fmac_f32_e32 v179, v9, v165
	v_fmac_f32_e32 v178, v9, v162
	v_fmac_f32_e32 v177, v9, v159
	v_fmac_f32_e32 v176, v9, v156
	v_fmac_f32_e32 v175, v9, v153
	v_fmac_f32_e32 v174, v9, v150
	v_fmac_f32_e32 v173, v9, v147
	v_fmac_f32_e32 v172, v9, v144
	v_fmac_f32_e32 v171, v9, v166
	v_fmac_f32_e32 v170, v9, v163
	v_fmac_f32_e32 v169, v9, v160
	v_fmac_f32_e32 v168, v9, v157
	v_fmac_f32_e32 v167, v9, v154
	v_fmac_f32_e32 v1, v9, v151
	v_fmac_f32_e32 v189, v8, v142
	v_fmac_f32_e32 v188, v8, v164
	v_fmac_f32_e32 v187, v8, v161
	v_fmac_f32_e32 v186, v8, v158
	v_fmac_f32_e32 v185, v8, v155
	v_fmac_f32_e32 v184, v8, v152
	v_fmac_f32_e32 v183, v8, v149
	v_fmac_f32_e32 v182, v8, v146
	v_fmac_f32_e32 v181, v8, v143
	v_fmac_f32_e32 v180, v8, v165
	v_fmac_f32_e32 v179, v8, v162
	v_fmac_f32_e32 v178, v8, v159
	v_fmac_f32_e32 v177, v8, v156
	v_fmac_f32_e32 v176, v8, v153
	v_fmac_f32_e32 v175, v8, v150
	v_fmac_f32_e32 v174, v8, v147
	v_fmac_f32_e32 v173, v8, v144
	v_fmac_f32_e32 v172, v8, v166
	v_fmac_f32_e32 v171, v8, v163
	v_fmac_f32_e32 v170, v8, v160
	v_fmac_f32_e32 v169, v8, v157
	v_fmac_f32_e32 v168, v8, v154
	v_fmac_f32_e32 v167, v8, v151
	v_fmac_f32_e32 v1, v8, v148
	v_fmac_f32_e32 v190, v7, v142
	v_fmac_f32_e32 v189, v7, v164
	v_fmac_f32_e32 v188, v7, v161
	v_fmac_f32_e32 v187, v7, v158
	v_fmac_f32_e32 v186, v7, v155
	v_fmac_f32_e32 v185, v7, v152
	v_fmac_f32_e32 v184, v7, v149
	v_fmac_f32_e32 v183, v7, v146
	v_fmac_f32_e32 v182, v7, v143
	v_fmac_f32_e32 v181, v7, v165
	v_fmac_f32_e32 v180, v7, v162
	v_fmac_f32_e32 v179, v7, v159
	v_fmac_f32_e32 v178, v7, v156
	v_fmac_f32_e32 v177, v7, v153
	v_fmac_f32_e32 v176, v7, v150
	v_fmac_f32_e32 v175, v7, v147
	v_fmac_f32_e32 v174, v7, v144
	v_fmac_f32_e32 v173, v7, v166
	v_fmac_f32_e32 v172, v7, v163
	v_fmac_f32_e32 v171, v7, v160
	v_fmac_f32_e32 v170, v7, v157
	v_fmac_f32_e32 v169, v7, v154
	v_fmac_f32_e32 v168, v7, v151
	v_fmac_f32_e32 v167, v7, v148
	v_fmac_f32_e32 v1, v7, v145
	v_fmac_f32_e32 v191, v6, v142
	v_fmac_f32_e32 v190, v6, v164
	v_fmac_f32_e32 v189, v6, v161
	v_fmac_f32_e32 v188, v6, v158
	v_fmac_f32_e32 v187, v6, v155
	v_fmac_f32_e32 v186, v6, v152
	v_fmac_f32_e32 v185, v6, v149
	v_fmac_f32_e32 v184, v6, v146
	v_fmac_f32_e32 v183, v6, v143
	v_fmac_f32_e32 v182, v6, v165
	v_fmac_f32_e32 v181, v6, v162
	v_fmac_f32_e32 v180, v6, v159
	v_fmac_f32_e32 v179, v6, v156
	v_fmac_f32_e32 v178, v6, v153
	v_fmac_f32_e32 v177, v6, v150
	v_fmac_f32_e32 v176, v6, v147
	v_fmac_f32_e32 v175, v6, v144
	v_fmac_f32_e32 v174, v6, v166
	v_fmac_f32_e32 v173, v6, v163
	v_fmac_f32_e32 v172, v6, v160
	v_fmac_f32_e32 v171, v6, v157
	v_fmac_f32_e32 v170, v6, v154
	v_fmac_f32_e32 v169, v6, v151
	v_fmac_f32_e32 v168, v6, v148
	v_fmac_f32_e32 v167, v6, v145
	v_fmac_f32_e32 v1, v6, v141
	v_fmac_f32_e32 v191, v5, v164
	v_fmac_f32_e32 v190, v5, v161
	v_fmac_f32_e32 v189, v5, v158
	v_fmac_f32_e32 v188, v5, v155
	v_fmac_f32_e32 v187, v5, v152
	v_fmac_f32_e32 v186, v5, v149
	v_fmac_f32_e32 v185, v5, v146
	v_fmac_f32_e32 v184, v5, v143
	v_fmac_f32_e32 v183, v5, v165
	v_fmac_f32_e32 v182, v5, v162
	v_fmac_f32_e32 v181, v5, v159
	v_fmac_f32_e32 v180, v5, v156
	v_fmac_f32_e32 v179, v5, v153
	v_fmac_f32_e32 v178, v5, v150
	v_fmac_f32_e32 v177, v5, v147
	v_fmac_f32_e32 v176, v5, v144
	v_fmac_f32_e32 v175, v5, v166
	v_fmac_f32_e32 v174, v5, v163
	v_fmac_f32_e32 v173, v5, v160
	v_fmac_f32_e32 v172, v5, v157
	v_fmac_f32_e32 v171, v5, v154
	v_fmac_f32_e32 v170, v5, v151
	v_fmac_f32_e32 v169, v5, v148
	v_fmac_f32_e32 v168, v5, v145
	v_fmac_f32_e32 v167, v5, v141
	v_fmac_f32_e32 v1, v5, v140
	v_fmac_f32_e32 v191, v4, v161
	v_fmac_f32_e32 v190, v4, v158
	v_fmac_f32_e32 v189, v4, v155
	v_fmac_f32_e32 v188, v4, v152
	v_fmac_f32_e32 v187, v4, v149
	v_fmac_f32_e32 v186, v4, v146
	v_fmac_f32_e32 v185, v4, v143
	v_fmac_f32_e32 v184, v4, v165
	v_fmac_f32_e32 v183, v4, v162
	v_fmac_f32_e32 v182, v4, v159
	v_fmac_f32_e32 v181, v4, v156
	v_fmac_f32_e32 v180, v4, v153
	v_fmac_f32_e32 v179, v4, v150
	v_fmac_f32_e32 v178, v4, v147
	v_fmac_f32_e32 v177, v4, v144
	v_fmac_f32_e32 v176, v4, v166
	v_fmac_f32_e32 v175, v4, v163
	v_fmac_f32_e32 v174, v4, v160
	v_fmac_f32_e32 v173, v4, v157
	v_fmac_f32_e32 v172, v4, v154
	v_fmac_f32_e32 v171, v4, v151
	v_fmac_f32_e32 v170, v4, v148
	v_fmac_f32_e32 v169, v4, v145
	v_fmac_f32_e32 v168, v4, v141
	v_fmac_f32_e32 v167, v4, v140
	v_fmac_f32_e32 v1, v4, v139
	v_fmac_f32_e32 v191, v3, v158
	v_fmac_f32_e32 v190, v3, v155
	v_fmac_f32_e32 v189, v3, v152
	v_fmac_f32_e32 v188, v3, v149
	v_fmac_f32_e32 v187, v3, v146
	v_fmac_f32_e32 v186, v3, v143
	v_fmac_f32_e32 v185, v3, v165
	v_fmac_f32_e32 v184, v3, v162
	v_fmac_f32_e32 v183, v3, v159
	v_fmac_f32_e32 v182, v3, v156
	v_fmac_f32_e32 v181, v3, v153
	v_fmac_f32_e32 v180, v3, v150
	v_fmac_f32_e32 v179, v3, v147
	v_fmac_f32_e32 v178, v3, v144
	v_fmac_f32_e32 v177, v3, v166
	v_fmac_f32_e32 v176, v3, v163
	v_fmac_f32_e32 v175, v3, v160
	v_fmac_f32_e32 v174, v3, v157
	v_fmac_f32_e32 v173, v3, v154
	v_fmac_f32_e32 v172, v3, v151
	v_fmac_f32_e32 v171, v3, v148
	v_fmac_f32_e32 v170, v3, v145
	v_fmac_f32_e32 v169, v3, v141
	v_fmac_f32_e32 v168, v3, v140
	v_fmac_f32_e32 v167, v3, v139
	v_fmac_f32_e32 v1, v3, v138
	v_fmac_f32_e32 v191, v2, v155
	v_fmac_f32_e32 v190, v2, v152
	v_fmac_f32_e32 v189, v2, v149
	v_fmac_f32_e32 v188, v2, v146
	v_fmac_f32_e32 v187, v2, v143
	v_fmac_f32_e32 v186, v2, v165
	v_fmac_f32_e32 v185, v2, v162
	v_fmac_f32_e32 v184, v2, v159
	v_fmac_f32_e32 v183, v2, v156
	v_fmac_f32_e32 v182, v2, v153
	v_fmac_f32_e32 v181, v2, v150
	v_fmac_f32_e32 v180, v2, v147
	v_fmac_f32_e32 v179, v2, v144
	v_fmac_f32_e32 v178, v2, v166
	v_fmac_f32_e32 v177, v2, v163
	v_fmac_f32_e32 v176, v2, v160
	v_fmac_f32_e32 v175, v2, v157
	v_fmac_f32_e32 v174, v2, v154
	v_fmac_f32_e32 v173, v2, v151
	v_fmac_f32_e32 v172, v2, v148
	v_fmac_f32_e32 v171, v2, v145
	v_fmac_f32_e32 v170, v2, v141
	v_fmac_f32_e32 v169, v2, v140
	v_fmac_f32_e32 v168, v2, v139
	v_fmac_f32_e32 v167, v2, v138
	v_fmac_f32_e32 v1, v2, v137
	v_fmac_f32_e32 v191, v0, v152
	v_fmac_f32_e32 v190, v0, v149
	v_fmac_f32_e32 v189, v0, v146
	v_fmac_f32_e32 v188, v0, v143
	v_fmac_f32_e32 v187, v0, v165
	v_fmac_f32_e32 v186, v0, v162
	v_fmac_f32_e32 v185, v0, v159
	v_fmac_f32_e32 v184, v0, v156
	v_fmac_f32_e32 v183, v0, v153
	v_fmac_f32_e32 v182, v0, v150
	v_fmac_f32_e32 v181, v0, v147
	v_fmac_f32_e32 v180, v0, v144
	v_fmac_f32_e32 v179, v0, v166
	v_fmac_f32_e32 v178, v0, v163
	v_fmac_f32_e32 v177, v0, v160
	v_fmac_f32_e32 v176, v0, v157
	v_fmac_f32_e32 v175, v0, v154
	v_fmac_f32_e32 v174, v0, v151
	v_fmac_f32_e32 v173, v0, v148
	v_fmac_f32_e32 v172, v0, v145
	v_fmac_f32_e32 v171, v0, v141
	v_fmac_f32_e32 v170, v0, v140
	v_fmac_f32_e32 v169, v0, v139
	v_fmac_f32_e32 v168, v0, v138
	v_fmac_f32_e32 v167, v0, v137
	v_fmac_f32_e32 v1, v0, v136
	ds_write2st64_b32 v116, v191, v190 offset0:48 offset1:56
	ds_write2st64_b32 v116, v189, v188 offset0:64 offset1:72
	ds_write2st64_b32 v116, v187, v186 offset0:80 offset1:88
	ds_write2st64_b32 v116, v185, v184 offset0:96 offset1:104
	ds_write2st64_b32 v116, v183, v182 offset0:112 offset1:120
	ds_write2st64_b32 v116, v181, v180 offset0:128 offset1:136
	ds_write2st64_b32 v116, v179, v178 offset0:144 offset1:152
	ds_write2st64_b32 v116, v177, v176 offset0:160 offset1:168
	ds_write2st64_b32 v116, v175, v174 offset0:176 offset1:184
	ds_write2st64_b32 v116, v173, v172 offset0:192 offset1:200
	ds_write2st64_b32 v116, v171, v170 offset0:208 offset1:216
	ds_write2st64_b32 v116, v169, v168 offset0:224 offset1:232
	ds_write2st64_b32 v116, v167, v1 offset0:240 offset1:248
.Lmy_conv_skip:
	s_cmp_ge_u32 s60, s13
	s_waitcnt lgkmcnt(0)
	s_barrier
	global_load_dwordx4 v[0:3], v[88:89], off offset:16
	global_load_dwordx4 v[8:11], v[88:89], off
	global_load_dwordx4 v[4:7], v[90:91], off offset:16
	global_load_dwordx4 v[12:15], v[90:91], off
	v_mbcnt_hi_u32_b32 v16, -1, v120
	s_cbranch_scc0 .LBB0_934
	s_cmp_ge_u32 s64, s13
	s_cbranch_scc0 .LBB0_935
